# k=1 weight transposes staggered: workgroups 128-191 run theirs before the GEMM units, 192-255 after (hand-written transposer)
# speedup vs baseline: 1.0032x; 1.0032x over previous
; __global__ void __launch_bounds__(NTHREADS) fwd_megakernel(Params p) {
;     ...
;         if (ph + 1 < p.ph_hi && need_bar) { if (p.ph_lo < 0) cg::this_grid().sync(); else xcd_barrier(gbar); }
;     }
.LBB0_667:
	s_or_b64 exec, exec, s[2:3]
	s_mov_b64 s[2:3], 0
	s_waitcnt lgkmcnt(0)
	s_barrier
.LBB0_668:
	s_branch .Ltr_pre
.Ltr_pre_ret:
	s_cbranch_vccz .LBB0_9
	s_waitcnt vmcnt(0) lgkmcnt(0)
	s_barrier
	s_mov_b64 s[2:3], exec
	v_readlane_b32 s6, v253, 53
	v_readlane_b32 s7, v253, 54
	s_and_b64 s[6:7], s[2:3], s[6:7]
	s_mov_b64 exec, s[6:7]
	s_cbranch_execz .LBB0_8
	v_readlane_b32 s6, v252, 2
	v_readlane_b32 s7, v252, 3
	buffer_wbl2 sc1
	s_load_dwordx2 s[6:7], s[6:7], 0x58
	s_mov_b64 s[8:9], exec
	v_mbcnt_lo_u32_b32 v1, s8, 0
	v_mbcnt_hi_u32_b32 v1, s9, v1
	v_cmp_eq_u32_e32 vcc, 0, v1
	s_waitcnt lgkmcnt(0)
	global_load_dword v0, v183, s[6:7] offset:40
	s_and_saveexec_b64 s[10:11], vcc
	s_cbranch_execz .LBB0_672
	s_bcnt1_i32_b64 s8, s[8:9]
	v_mov_b32_e32 v2, s8
	global_atomic_add v2, v183, v2, s[6:7] offset:32 sc0

; __device__ __forceinline__ int opaque_tid() { int t = threadIdx.x; asm volatile("" : "+v"(t)); return t; }
; __global__ void __launch_bounds__(NTHREADS) fwd_megakernel(Params p) {
;     ...
;             if (k == 1 && gridDim.x == 256 && S.c >= 128) { __syncthreads(); const int t_ = opaque_tid(); const int gw_ = (S.c - 128) * NWAVES + (t_ >> 6);
;                 transpose_range(p, lds, l, TI_IN, TI_IN + TI_OUT + TI_UP, gw_, 128 * NWAVES, t_ >> 6, t_ & 63);
;                 if (l + 1 < DEPTH) transpose_range(p, lds, l + 1, 0, TI_IN, gw_, 128 * NWAVES, t_ >> 6, t_ & 63); }
.Ltr_pre:
	s_mov_b32 s100, 0x4040404
	s_bitcmp1_b32 s100, s90
	s_cbranch_scc0 .Ltr_pre_skip
	s_cmp_gt_i32 s90, 31
	s_cbranch_scc1 .Ltr_pre_skip
	s_cmpk_lt_u32 s63, 0x80
	s_cbranch_scc1 .Ltr_pre_skip
	s_cmpk_lt_u32 s63, 0xc0
	s_cbranch_scc0 .Ltr_pre_skip
	s_mov_b64 s[48:49], s[2:3]
	s_mov_b32 s50, 1
	s_branch .Ltr_common
.Ltr_pre_skip:
	s_and_b64 vcc, exec, s[2:3]
	s_branch .Ltr_pre_ret
.Ltr_begin:
	s_cmp_eq_u32 s90, 2
	s_cbranch_scc1 .Ltr_begin_all
	s_cmpk_lt_u32 s63, 0xc0
	s_cbranch_scc1 .LBB0_553
.Ltr_begin_all:
	s_mov_b32 s50, 0
.Ltr_common:
	s_waitcnt vmcnt(0) lgkmcnt(0)
	s_barrier
	v_readlane_b32 s0, v252, 2
	v_readlane_b32 s1, v252, 3
	s_nop 0
	s_sub_u32 s0, s0, 0x90
	s_subb_u32 s1, s1, 0
	s_load_dwordx2 s[40:41], s[0:1], 0x8
	s_load_dwordx2 s[36:37], s[0:1], 0x30
	s_load_dwordx2 s[38:39], s[0:1], 0x48
	s_add_i32 s13, s90, -1
	s_lshr_b32 s13, s13, 3
	v_lshrrev_b32_e32 v142, 6, v185
	v_and_b32_e32 v143, 63, v185
	v_readfirstlane_b32 s12, v142
	s_sub_i32 s11, s63, 0x80
	s_lshl_b32 s11, s11, 3
	s_add_i32 s11, s11, s12
	s_mul_i32 s12, s12, 0x4100
	v_lshrrev_b32_e32 v129, 4, v143
	v_and_b32_e32 v130, 15, v143
	v_mul_u32_u24_e32 v131, 0x104, v129
	v_lshl_add_u32 v131, v130, 4, v131
	v_add_u32_e32 v131, s12, v131
	v_lshlrev_b32_e32 v130, 4, v130
	v_and_b32_e32 v142, 7, v143
	v_lshrrev_b32_e32 v143, 3, v143
	v_mul_u32_u24_e32 v132, 0x820, v142
	v_lshl_add_u32 v132, v143, 2, v132
	v_add_u32_e32 v132, s12, v132
	v_lshlrev_b32_e32 v134, 12, v143
	v_lshl_add_u32 v134, v142, 4, v134
	v_add_u32_e32 v135, 0x8000, v134
	v_add_u32_e32 v136, 0x10000, v134
	v_add_u32_e32 v137, 0x18000, v134
	v_add_u32_e32 v138, 0x20000, v134
	v_add_u32_e32 v139, 0x28000, v134
	v_add_u32_e32 v140, 0x30000, v134
	v_add_u32_e32 v141, 0x38000, v134
	s_mov_b32 s9, 0
	s_mov_b32 s10, s11
	s_waitcnt lgkmcnt(0)
	s_cmp_lg_u32 s9, 0
	s_cbranch_scc1 .Ltr_n0_p1
	s_cmpk_lt_u32 s10, 0x1a00
	s_cbranch_scc0 .Ltr_n0_to1
	s_cmpk_lt_u32 s10, 0x400
	s_cbranch_scc0 .Ltr_n0_up
	s_lshr_b32 s42, s10, 5
	s_and_b32 s43, s10, 31
	s_movk_i32 s8, 0x2000
	s_lshl_b32 s0, s13, 24
	s_add_u32 s0, s36, s0
	s_addc_u32 s1, s37, 0
	s_lshl_b32 s2, s13, 23
	s_add_u32 s2, s2, 0x5000000
	s_branch .Ltr_n0_fin

; __device__ __forceinline__ int opaque_tid() { int t = threadIdx.x; asm volatile("" : "+v"(t)); return t; }
; __global__ void __launch_bounds__(NTHREADS) fwd_megakernel(Params p) {
;     ...
;             if (k == 1 && gridDim.x == 256 && S.c >= 128) { __syncthreads(); const int t_ = opaque_tid(); const int gw_ = (S.c - 128) * NWAVES + (t_ >> 6);
;                 transpose_range(p, lds, l, TI_IN, TI_IN + TI_OUT + TI_UP, gw_, 128 * NWAVES, t_ >> 6, t_ & 63);
;                 if (l + 1 < DEPTH) transpose_range(p, lds, l + 1, 0, TI_IN, gw_, 128 * NWAVES, t_ >> 6, t_ & 63); }
;     ...
;         if (ph + 1 < p.ph_hi && need_bar) { if (p.ph_lo < 0) cg::this_grid().sync(); else xcd_barrier(gbar); }
;     }
.Ltr_exit:
	s_cmp_eq_u32 s50, 1
	s_cbranch_scc0 .Ltr_exit_post
	s_waitcnt lgkmcnt(0)
	s_barrier
	s_mov_b64 s[2:3], s[48:49]
	s_cmp_ge_i32 s90, s91
	s_cselect_b64 s[0:1], -1, 0
	v_readlane_b32 s36, v253, 55
	v_readlane_b32 s37, v253, 56
	v_readlane_b32 s38, v253, 57
	v_readlane_b32 s39, v253, 58
	v_readlane_b32 s40, v253, 59
	v_readlane_b32 s41, v253, 60
	v_readlane_b32 s42, v253, 61
	v_readlane_b32 s43, v253, 62
	v_readlane_b32 s44, v253, 63
	v_readlane_b32 s45, v254, 0
	v_readlane_b32 s46, v254, 1
	v_readlane_b32 s47, v254, 2
	v_readlane_b32 s48, v254, 3
	v_readlane_b32 s49, v254, 4
	v_readlane_b32 s50, v254, 5
	v_readlane_b32 s51, v254, 6
	s_and_b64 vcc, exec, s[2:3]
	s_branch .Ltr_pre_ret
